# dense attention: third round of pair-units split by query half over 64 blocks (four waves compute, the other four only stage K/V), two full pair-units per block
# speedup vs baseline: 1.0121x; 1.0085x over previous
.Lga_entry:
	s_mov_b64 exec, -1
	s_load_dwordx2 s[4:5], s[64:65], 0xf8
	s_mov_b32 s100, 0x3e38aa3b
	s_mov_b32 s101, 0
	v_mov_b32_e32 v86, 0x3e38aa3b
	v_and_b32_e32 v144, 63, v247
	v_lshrrev_b32_e32 v145, 6, v247
	v_and_b32_e32 v146, 15, v144
	v_lshrrev_b32_e32 v147, 4, v144
	v_readfirstlane_b32 s21, v145
	v_bfe_u32 v148, v146, 1, 3
	v_lshlrev_b32_e32 v149, 7, v146
	v_xor_b32_e32 v150, v147, v148
	v_lshl_add_u32 v136, v150, 4, v149
	v_add_u32_e32 v136, 16, v136
	v_xor_b32_e32 v150, 4, v150
	v_lshl_add_u32 v137, v150, 4, v149
	v_add_u32_e32 v137, 16, v137
	v_lshrrev_b32_e32 v151, 1, v147
	v_and_b32_e32 v152, 1, v147
	v_lshlrev_b32_e32 v152, 3, v152
	v_add_u32_e32 v152, v152, v149
	v_add_u32_e32 v152, 0x2010, v152
	v_add_u32_e32 v153, 0, v151
	v_xor_b32_e32 v153, v153, v148
	v_lshl_add_u32 v138, v153, 4, v152
	v_add_u32_e32 v153, 2, v151
	v_xor_b32_e32 v153, v153, v148
	v_lshl_add_u32 v139, v153, 4, v152
	v_add_u32_e32 v153, 4, v151
	v_xor_b32_e32 v153, v153, v148
	v_lshl_add_u32 v140, v153, 4, v152
	v_add_u32_e32 v153, 6, v151
	v_xor_b32_e32 v153, v153, v148
	v_lshl_add_u32 v141, v153, 4, v152
	s_lshl_b32 s0, s21, 3
	v_lshrrev_b32_e32 v153, 3, v144
	v_add_u32_e32 v153, s0, v153
	v_bfe_u32 v154, v153, 1, 3
	v_and_b32_e32 v155, 7, v144
	v_xor_b32_e32 v154, v154, v155
	v_lshlrev_b32_e32 v154, 4, v154
	v_mul_u32_u24_e32 v142, 0x3000, v153
	v_add_u32_e32 v142, v142, v154
	v_mul_u32_u24_e32 v143, 0x9000, v153
	v_add_u32_e32 v143, v143, v154
	s_lshl_b32 s32, s21, 10
	s_add_u32 s32, s32, 16
	s_add_u32 s41, s32, 0x2000
	s_sub_u32 s1, s40, 144
	s_waitcnt lgkmcnt(0)

.Lga_go0:
	s_bitcmp1_b32 s101, 0
	s_cbranch_scc1 .Lga_idle0
	ds_read_b128 v[18:21], v136 offset:0
	ds_read_b128 v[22:25], v137 offset:0
	ds_read_b128 v[26:29], v136 offset:2048
	ds_read_b128 v[30:33], v137 offset:2048
	ds_read_b128 v[34:37], v136 offset:4096
	ds_read_b128 v[38:41], v137 offset:4096
	ds_read_b128 v[42:45], v136 offset:6144
	ds_read_b128 v[46:49], v137 offset:6144
	s_waitcnt lgkmcnt(0)
	v_mfma_f32_16x16x32_bf16 v[50:53], v[18:21], v[2:5], 0
	v_mfma_f32_16x16x32_bf16 v[54:57], v[26:29], v[2:5], 0
	v_mfma_f32_16x16x32_bf16 v[58:61], v[34:37], v[2:5], 0
	v_mfma_f32_16x16x32_bf16 v[62:65], v[42:45], v[2:5], 0
	v_mfma_f32_16x16x32_bf16 v[50:53], v[22:25], v[6:9], v[50:53]
	v_mfma_f32_16x16x32_bf16 v[54:57], v[30:33], v[6:9], v[54:57]
	v_mfma_f32_16x16x32_bf16 v[58:61], v[38:41], v[6:9], v[58:61]
	v_mfma_f32_16x16x32_bf16 v[62:65], v[46:49], v[6:9], v[62:65]
	ds_read_b64 v[168:169], v138 offset:0
	ds_read_b64 v[170:171], v139 offset:0
	ds_read_b64 v[172:173], v140 offset:0
	ds_read_b64 v[174:175], v141 offset:0
	ds_read_b64 v[176:177], v138 offset:2048
	ds_read_b64 v[178:179], v139 offset:2048
	ds_read_b64 v[180:181], v140 offset:2048
	ds_read_b64 v[182:183], v141 offset:2048
	v_mfma_f32_16x16x32_bf16 v[66:69], v[18:21], v[10:13], 0
	v_mfma_f32_16x16x32_bf16 v[70:73], v[26:29], v[10:13], 0
	v_mfma_f32_16x16x32_bf16 v[74:77], v[34:37], v[10:13], 0
	v_mfma_f32_16x16x32_bf16 v[78:81], v[42:45], v[10:13], 0
	v_mfma_f32_16x16x32_bf16 v[66:69], v[22:25], v[14:17], v[66:69]
	v_mfma_f32_16x16x32_bf16 v[70:73], v[30:33], v[14:17], v[70:73]
	v_mfma_f32_16x16x32_bf16 v[74:77], v[38:41], v[14:17], v[74:77]
	v_mfma_f32_16x16x32_bf16 v[78:81], v[46:49], v[14:17], v[78:81]
	ds_read_b64 v[184:185], v138 offset:4096
	ds_read_b64 v[186:187], v139 offset:4096
	ds_read_b64 v[188:189], v140 offset:4096
	ds_read_b64 v[190:191], v141 offset:4096
	ds_read_b64 v[192:193], v138 offset:6144
	ds_read_b64 v[194:195], v139 offset:6144
	ds_read_b64 v[196:197], v140 offset:6144
	ds_read_b64 v[198:199], v141 offset:6144
	s_nop 3
	v_max3_f32 v144, v50, v51, v52
	v_max3_f32 v145, v53, v54, v55
	v_max3_f32 v150, v56, v57, v58
	v_max3_f32 v151, v59, v60, v61
	v_max3_f32 v152, v62, v63, v64
	v_max3_f32 v144, v144, v145, v65
	v_max3_f32 v144, v144, v150, v151
	v_max_f32_e32 v144, v144, v152
	v_mov_b32_e32 v145, v144
	s_nop 1
	v_permlane16_swap_b32_e32 v144, v145
	v_max_f32_e32 v144, v144, v145
	v_mov_b32_e32 v145, v144
	s_nop 1
	v_permlane32_swap_b32_e32 v144, v145
	v_max_f32_e32 v144, v144, v145
	v_mul_f32_e32 v144, s100, v144
	v_max_f32_e32 v146, v132, v144
	v_cmp_gt_f32_e32 vcc, v146, v132
	s_cbranch_vccz .Lga_nors1
	v_sub_f32_e32 v148, v132, v146
	v_exp_f32_e32 v148, v148
	v_mov_b32_e32 v132, v146
	s_nop 0
	v_mul_f32_e32 v134, v134, v148
	v_pk_mul_f32 v[100:101], v[100:101], v[148:149] op_sel_hi:[1,0]
	v_pk_mul_f32 v[102:103], v[102:103], v[148:149] op_sel_hi:[1,0]
	v_pk_mul_f32 v[104:105], v[104:105], v[148:149] op_sel_hi:[1,0]
	v_pk_mul_f32 v[106:107], v[106:107], v[148:149] op_sel_hi:[1,0]
	v_pk_mul_f32 v[108:109], v[108:109], v[148:149] op_sel_hi:[1,0]
	v_pk_mul_f32 v[110:111], v[110:111], v[148:149] op_sel_hi:[1,0]
	v_pk_mul_f32 v[112:113], v[112:113], v[148:149] op_sel_hi:[1,0]
	v_pk_mul_f32 v[114:115], v[114:115], v[148:149] op_sel_hi:[1,0]

.Lga_idle0:
	s_sub_u32 s42, s42, 1
	s_cmp_lt_u32 s42, 3
	s_cbranch_scc1 .Lga_tail1
	s_waitcnt vmcnt(4)
	s_barrier
	s_cmp_lt_u32 s42, 4
	s_cbranch_scc1 .Lga_go1
	s_cmp_eq_u32 s89, 4
	s_cbranch_scc0 .Lga_nosw5
	s_mov_b64 s[6:7], s[96:97]
	s_mov_b64 s[8:9], s[98:99]

.Lga_go1:
	s_bitcmp1_b32 s101, 0
	s_cbranch_scc1 .Lga_idle1
	ds_read_b128 v[18:21], v136 offset:16384
	ds_read_b128 v[22:25], v137 offset:16384
	ds_read_b128 v[26:29], v136 offset:18432
	ds_read_b128 v[30:33], v137 offset:18432
	ds_read_b128 v[34:37], v136 offset:20480
	ds_read_b128 v[38:41], v137 offset:20480
	ds_read_b128 v[42:45], v136 offset:22528
	ds_read_b128 v[46:49], v137 offset:22528
	s_waitcnt lgkmcnt(0)
	v_mfma_f32_16x16x32_bf16 v[50:53], v[18:21], v[2:5], 0
	v_mfma_f32_16x16x32_bf16 v[54:57], v[26:29], v[2:5], 0
	v_mfma_f32_16x16x32_bf16 v[58:61], v[34:37], v[2:5], 0
	v_mfma_f32_16x16x32_bf16 v[62:65], v[42:45], v[2:5], 0
	v_mfma_f32_16x16x32_bf16 v[50:53], v[22:25], v[6:9], v[50:53]
	v_mfma_f32_16x16x32_bf16 v[54:57], v[30:33], v[6:9], v[54:57]
	v_mfma_f32_16x16x32_bf16 v[58:61], v[38:41], v[6:9], v[58:61]
	v_mfma_f32_16x16x32_bf16 v[62:65], v[46:49], v[6:9], v[62:65]
	ds_read_b64 v[168:169], v138 offset:16384
	ds_read_b64 v[170:171], v139 offset:16384
	ds_read_b64 v[172:173], v140 offset:16384
	ds_read_b64 v[174:175], v141 offset:16384
	ds_read_b64 v[176:177], v138 offset:18432
	ds_read_b64 v[178:179], v139 offset:18432
	ds_read_b64 v[180:181], v140 offset:18432
	ds_read_b64 v[182:183], v141 offset:18432
	v_mfma_f32_16x16x32_bf16 v[66:69], v[18:21], v[10:13], 0
	v_mfma_f32_16x16x32_bf16 v[70:73], v[26:29], v[10:13], 0
	v_mfma_f32_16x16x32_bf16 v[74:77], v[34:37], v[10:13], 0
	v_mfma_f32_16x16x32_bf16 v[78:81], v[42:45], v[10:13], 0
	v_mfma_f32_16x16x32_bf16 v[66:69], v[22:25], v[14:17], v[66:69]
	v_mfma_f32_16x16x32_bf16 v[70:73], v[30:33], v[14:17], v[70:73]
	v_mfma_f32_16x16x32_bf16 v[74:77], v[38:41], v[14:17], v[74:77]
	v_mfma_f32_16x16x32_bf16 v[78:81], v[46:49], v[14:17], v[78:81]
	ds_read_b64 v[184:185], v138 offset:20480
	ds_read_b64 v[186:187], v139 offset:20480
	ds_read_b64 v[188:189], v140 offset:20480
	ds_read_b64 v[190:191], v141 offset:20480
	ds_read_b64 v[192:193], v138 offset:22528
	ds_read_b64 v[194:195], v139 offset:22528
	ds_read_b64 v[196:197], v140 offset:22528
	ds_read_b64 v[198:199], v141 offset:22528
	s_nop 3
	v_max3_f32 v144, v50, v51, v52
	v_max3_f32 v145, v53, v54, v55
	v_max3_f32 v150, v56, v57, v58
	v_max3_f32 v151, v59, v60, v61
	v_max3_f32 v152, v62, v63, v64
	v_max3_f32 v144, v144, v145, v65
	v_max3_f32 v144, v144, v150, v151
	v_max_f32_e32 v144, v144, v152
	v_mov_b32_e32 v145, v144
	s_nop 1
	v_permlane16_swap_b32_e32 v144, v145
	v_max_f32_e32 v144, v144, v145
	v_mov_b32_e32 v145, v144
	s_nop 1
	v_permlane32_swap_b32_e32 v144, v145
	v_max_f32_e32 v144, v144, v145
	v_mul_f32_e32 v144, s100, v144
	v_max_f32_e32 v146, v132, v144
	v_cmp_gt_f32_e32 vcc, v146, v132
	s_cbranch_vccz .Lga_nors3
	v_sub_f32_e32 v148, v132, v146
	v_exp_f32_e32 v148, v148
	v_mov_b32_e32 v132, v146
	s_nop 0
	v_mul_f32_e32 v134, v134, v148
	v_pk_mul_f32 v[100:101], v[100:101], v[148:149] op_sel_hi:[1,0]
	v_pk_mul_f32 v[102:103], v[102:103], v[148:149] op_sel_hi:[1,0]
	v_pk_mul_f32 v[104:105], v[104:105], v[148:149] op_sel_hi:[1,0]
	v_pk_mul_f32 v[106:107], v[106:107], v[148:149] op_sel_hi:[1,0]
	v_pk_mul_f32 v[108:109], v[108:109], v[148:149] op_sel_hi:[1,0]
	v_pk_mul_f32 v[110:111], v[110:111], v[148:149] op_sel_hi:[1,0]
	v_pk_mul_f32 v[112:113], v[112:113], v[148:149] op_sel_hi:[1,0]
	v_pk_mul_f32 v[114:115], v[114:115], v[148:149] op_sel_hi:[1,0]

.Lga_go2:
	s_bitcmp1_b32 s101, 0
	s_cbranch_scc1 .Lga_idle2
	ds_read_b128 v[18:21], v136 offset:32768
	ds_read_b128 v[22:25], v137 offset:32768
	ds_read_b128 v[26:29], v136 offset:34816
	ds_read_b128 v[30:33], v137 offset:34816
	ds_read_b128 v[34:37], v136 offset:36864
	ds_read_b128 v[38:41], v137 offset:36864
	ds_read_b128 v[42:45], v136 offset:38912
	ds_read_b128 v[46:49], v137 offset:38912
	s_waitcnt lgkmcnt(0)
	v_mfma_f32_16x16x32_bf16 v[50:53], v[18:21], v[2:5], 0
	v_mfma_f32_16x16x32_bf16 v[54:57], v[26:29], v[2:5], 0
	v_mfma_f32_16x16x32_bf16 v[58:61], v[34:37], v[2:5], 0
	v_mfma_f32_16x16x32_bf16 v[62:65], v[42:45], v[2:5], 0
	v_mfma_f32_16x16x32_bf16 v[50:53], v[22:25], v[6:9], v[50:53]
	v_mfma_f32_16x16x32_bf16 v[54:57], v[30:33], v[6:9], v[54:57]
	v_mfma_f32_16x16x32_bf16 v[58:61], v[38:41], v[6:9], v[58:61]
	v_mfma_f32_16x16x32_bf16 v[62:65], v[46:49], v[6:9], v[62:65]
	ds_read_b64 v[168:169], v138 offset:32768
	ds_read_b64 v[170:171], v139 offset:32768
	ds_read_b64 v[172:173], v140 offset:32768
	ds_read_b64 v[174:175], v141 offset:32768
	ds_read_b64 v[176:177], v138 offset:34816
	ds_read_b64 v[178:179], v139 offset:34816
	ds_read_b64 v[180:181], v140 offset:34816
	ds_read_b64 v[182:183], v141 offset:34816
	v_mfma_f32_16x16x32_bf16 v[66:69], v[18:21], v[10:13], 0
	v_mfma_f32_16x16x32_bf16 v[70:73], v[26:29], v[10:13], 0
	v_mfma_f32_16x16x32_bf16 v[74:77], v[34:37], v[10:13], 0
	v_mfma_f32_16x16x32_bf16 v[78:81], v[42:45], v[10:13], 0
	v_mfma_f32_16x16x32_bf16 v[66:69], v[22:25], v[14:17], v[66:69]
	v_mfma_f32_16x16x32_bf16 v[70:73], v[30:33], v[14:17], v[70:73]
	v_mfma_f32_16x16x32_bf16 v[74:77], v[38:41], v[14:17], v[74:77]
	v_mfma_f32_16x16x32_bf16 v[78:81], v[46:49], v[14:17], v[78:81]
	ds_read_b64 v[184:185], v138 offset:36864
	ds_read_b64 v[186:187], v139 offset:36864
	ds_read_b64 v[188:189], v140 offset:36864
	ds_read_b64 v[190:191], v141 offset:36864
	ds_read_b64 v[192:193], v138 offset:38912
	ds_read_b64 v[194:195], v139 offset:38912
	ds_read_b64 v[196:197], v140 offset:38912
	ds_read_b64 v[198:199], v141 offset:38912
	s_nop 3
	v_max3_f32 v144, v50, v51, v52
	v_max3_f32 v145, v53, v54, v55
	v_max3_f32 v150, v56, v57, v58
	v_max3_f32 v151, v59, v60, v61
	v_max3_f32 v152, v62, v63, v64
	v_max3_f32 v144, v144, v145, v65
	v_max3_f32 v144, v144, v150, v151
	v_max_f32_e32 v144, v144, v152
	v_mov_b32_e32 v145, v144
	s_nop 1
	v_permlane16_swap_b32_e32 v144, v145
	v_max_f32_e32 v144, v144, v145
	v_mov_b32_e32 v145, v144
	s_nop 1
	v_permlane32_swap_b32_e32 v144, v145
	v_max_f32_e32 v144, v144, v145
	v_mul_f32_e32 v144, s100, v144
	v_max_f32_e32 v146, v132, v144
	v_cmp_gt_f32_e32 vcc, v146, v132
	s_cbranch_vccz .Lga_nors5
	v_sub_f32_e32 v148, v132, v146
	v_exp_f32_e32 v148, v148
	v_mov_b32_e32 v132, v146
	s_nop 0
	v_mul_f32_e32 v134, v134, v148
	v_pk_mul_f32 v[100:101], v[100:101], v[148:149] op_sel_hi:[1,0]
	v_pk_mul_f32 v[102:103], v[102:103], v[148:149] op_sel_hi:[1,0]
	v_pk_mul_f32 v[104:105], v[104:105], v[148:149] op_sel_hi:[1,0]
	v_pk_mul_f32 v[106:107], v[106:107], v[148:149] op_sel_hi:[1,0]
	v_pk_mul_f32 v[108:109], v[108:109], v[148:149] op_sel_hi:[1,0]
	v_pk_mul_f32 v[110:111], v[110:111], v[148:149] op_sel_hi:[1,0]
	v_pk_mul_f32 v[112:113], v[112:113], v[148:149] op_sel_hi:[1,0]
	v_pk_mul_f32 v[114:115], v[114:115], v[148:149] op_sel_hi:[1,0]

.Lga_go3:
	s_bitcmp1_b32 s101, 0
	s_cbranch_scc1 .Lga_idle3
	ds_read_b128 v[18:21], v136 offset:49152
	ds_read_b128 v[22:25], v137 offset:49152
	ds_read_b128 v[26:29], v136 offset:51200
	ds_read_b128 v[30:33], v137 offset:51200
	ds_read_b128 v[34:37], v136 offset:53248
	ds_read_b128 v[38:41], v137 offset:53248
	ds_read_b128 v[42:45], v136 offset:55296
	ds_read_b128 v[46:49], v137 offset:55296
	s_waitcnt lgkmcnt(0)
	v_mfma_f32_16x16x32_bf16 v[50:53], v[18:21], v[2:5], 0
	v_mfma_f32_16x16x32_bf16 v[54:57], v[26:29], v[2:5], 0
	v_mfma_f32_16x16x32_bf16 v[58:61], v[34:37], v[2:5], 0
	v_mfma_f32_16x16x32_bf16 v[62:65], v[42:45], v[2:5], 0
	v_mfma_f32_16x16x32_bf16 v[50:53], v[22:25], v[6:9], v[50:53]
	v_mfma_f32_16x16x32_bf16 v[54:57], v[30:33], v[6:9], v[54:57]
	v_mfma_f32_16x16x32_bf16 v[58:61], v[38:41], v[6:9], v[58:61]
	v_mfma_f32_16x16x32_bf16 v[62:65], v[46:49], v[6:9], v[62:65]
	ds_read_b64 v[168:169], v138 offset:49152
	ds_read_b64 v[170:171], v139 offset:49152
	ds_read_b64 v[172:173], v140 offset:49152
	ds_read_b64 v[174:175], v141 offset:49152
	ds_read_b64 v[176:177], v138 offset:51200
	ds_read_b64 v[178:179], v139 offset:51200
	ds_read_b64 v[180:181], v140 offset:51200
	ds_read_b64 v[182:183], v141 offset:51200
	v_mfma_f32_16x16x32_bf16 v[66:69], v[18:21], v[10:13], 0
	v_mfma_f32_16x16x32_bf16 v[70:73], v[26:29], v[10:13], 0
	v_mfma_f32_16x16x32_bf16 v[74:77], v[34:37], v[10:13], 0
	v_mfma_f32_16x16x32_bf16 v[78:81], v[42:45], v[10:13], 0
	v_mfma_f32_16x16x32_bf16 v[66:69], v[22:25], v[14:17], v[66:69]
	v_mfma_f32_16x16x32_bf16 v[70:73], v[30:33], v[14:17], v[70:73]
	v_mfma_f32_16x16x32_bf16 v[74:77], v[38:41], v[14:17], v[74:77]
	v_mfma_f32_16x16x32_bf16 v[78:81], v[46:49], v[14:17], v[78:81]
	ds_read_b64 v[184:185], v138 offset:53248
	ds_read_b64 v[186:187], v139 offset:53248
	ds_read_b64 v[188:189], v140 offset:53248
	ds_read_b64 v[190:191], v141 offset:53248
	ds_read_b64 v[192:193], v138 offset:55296
	ds_read_b64 v[194:195], v139 offset:55296
	ds_read_b64 v[196:197], v140 offset:55296
	ds_read_b64 v[198:199], v141 offset:55296
	s_nop 3
	v_max3_f32 v144, v50, v51, v52
	v_max3_f32 v145, v53, v54, v55
	v_max3_f32 v150, v56, v57, v58
	v_max3_f32 v151, v59, v60, v61
	v_max3_f32 v152, v62, v63, v64
	v_max3_f32 v144, v144, v145, v65
	v_max3_f32 v144, v144, v150, v151
	v_max_f32_e32 v144, v144, v152
	v_mov_b32_e32 v145, v144
	s_nop 1
	v_permlane16_swap_b32_e32 v144, v145
	v_max_f32_e32 v144, v144, v145
	v_mov_b32_e32 v145, v144
	s_nop 1
	v_permlane32_swap_b32_e32 v144, v145
	v_max_f32_e32 v144, v144, v145
	v_mul_f32_e32 v144, s100, v144
	v_max_f32_e32 v146, v132, v144
	v_cmp_gt_f32_e32 vcc, v146, v132
	s_cbranch_vccz .Lga_nors7
	v_sub_f32_e32 v148, v132, v146
	v_exp_f32_e32 v148, v148
	v_mov_b32_e32 v132, v146
	s_nop 0
	v_mul_f32_e32 v134, v134, v148
	v_pk_mul_f32 v[100:101], v[100:101], v[148:149] op_sel_hi:[1,0]
	v_pk_mul_f32 v[102:103], v[102:103], v[148:149] op_sel_hi:[1,0]
	v_pk_mul_f32 v[104:105], v[104:105], v[148:149] op_sel_hi:[1,0]
	v_pk_mul_f32 v[106:107], v[106:107], v[148:149] op_sel_hi:[1,0]
	v_pk_mul_f32 v[108:109], v[108:109], v[148:149] op_sel_hi:[1,0]
	v_pk_mul_f32 v[110:111], v[110:111], v[148:149] op_sel_hi:[1,0]
	v_pk_mul_f32 v[112:113], v[112:113], v[148:149] op_sel_hi:[1,0]
	v_pk_mul_f32 v[114:115], v[114:115], v[148:149] op_sel_hi:[1,0]

.Lga_idle3:
	s_sub_u32 s42, s42, 1
	s_cmp_eq_u32 s42, 0
	s_cbranch_scc0 .Lga_loop
	s_bitcmp1_b32 s101, 0
	s_cbranch_scc1 .Lga_nostore
	s_nop 7
	s_nop 1
	v_mov_b32_e32 v145, v134
	s_nop 1
	v_permlane16_swap_b32_e32 v134, v145
	v_add_f32_e32 v134, v134, v145
	v_mov_b32_e32 v145, v134
	s_nop 1
	v_permlane32_swap_b32_e32 v134, v145
	v_add_f32_e32 v134, v134, v145
	v_rcp_f32_e32 v134, v134
	s_nop 0
	v_mul_f32_e32 v100, v100, v134
	v_mul_f32_e32 v101, v101, v134
	v_mul_f32_e32 v102, v102, v134
	v_mul_f32_e32 v103, v103, v134
	v_mul_f32_e32 v104, v104, v134
	v_mul_f32_e32 v105, v105, v134
	v_mul_f32_e32 v106, v106, v134
	v_mul_f32_e32 v107, v107, v134
	v_mul_f32_e32 v108, v108, v134
	v_mul_f32_e32 v109, v109, v134
	v_mul_f32_e32 v110, v110, v134
	v_mul_f32_e32 v111, v111, v134
	v_mul_f32_e32 v112, v112, v134
	v_mul_f32_e32 v113, v113, v134
	v_mul_f32_e32 v114, v114, v134
	v_mul_f32_e32 v115, v115, v134
	v_cvt_pk_bf16_f32 v146, v100, v101
	v_cvt_pk_bf16_f32 v147, v102, v103
	v_cvt_pk_bf16_f32 v148, v104, v105
	v_cvt_pk_bf16_f32 v149, v106, v107
	v_cvt_pk_bf16_f32 v150, v108, v109
	v_cvt_pk_bf16_f32 v151, v110, v111
	v_cvt_pk_bf16_f32 v152, v112, v113
	v_cvt_pk_bf16_f32 v153, v114, v115
	global_store_dwordx2 v[84:85], v[146:147], off offset:0
	global_store_dwordx2 v[84:85], v[148:149], off offset:32
	global_store_dwordx2 v[84:85], v[150:151], off offset:64
	global_store_dwordx2 v[84:85], v[152:153], off offset:96
	v_mov_b32_e32 v145, v135
	s_nop 1
	v_permlane16_swap_b32_e32 v135, v145
	v_add_f32_e32 v135, v135, v145
	v_mov_b32_e32 v145, v135
	s_nop 1
	v_permlane32_swap_b32_e32 v135, v145
	v_add_f32_e32 v135, v135, v145
	v_rcp_f32_e32 v135, v135
	s_nop 0
	v_mul_f32_e32 v116, v116, v135
	v_mul_f32_e32 v117, v117, v135
	v_mul_f32_e32 v118, v118, v135
	v_mul_f32_e32 v119, v119, v135
	v_mul_f32_e32 v120, v120, v135
	v_mul_f32_e32 v121, v121, v135
	v_mul_f32_e32 v122, v122, v135
	v_mul_f32_e32 v123, v123, v135
	v_mul_f32_e32 v124, v124, v135
	v_mul_f32_e32 v125, v125, v135
	v_mul_f32_e32 v126, v126, v135
	v_mul_f32_e32 v127, v127, v135
	v_mul_f32_e32 v128, v128, v135
	v_mul_f32_e32 v129, v129, v135
	v_mul_f32_e32 v130, v130, v135
	v_mul_f32_e32 v131, v131, v135
	v_cvt_pk_bf16_f32 v146, v116, v117
	v_cvt_pk_bf16_f32 v147, v118, v119
	v_cvt_pk_bf16_f32 v148, v120, v121
	v_cvt_pk_bf16_f32 v149, v122, v123
	v_cvt_pk_bf16_f32 v150, v124, v125
	v_cvt_pk_bf16_f32 v151, v126, v127
	v_cvt_pk_bf16_f32 v152, v128, v129
	v_cvt_pk_bf16_f32 v153, v130, v131
	global_store_dwordx2 v[84:85], v[146:147], off offset:128
	global_store_dwordx2 v[84:85], v[148:149], off offset:160
	global_store_dwordx2 v[84:85], v[150:151], off offset:192
	global_store_dwordx2 v[84:85], v[152:153], off offset:224
.Lga_nostore:
	s_bitcmp1_b32 s101, 1
	s_cbranch_scc1 .Lga_done
	s_add_u32 s1, s1, 0x70
	s_cmpk_lt_u32 s1, 0xe0
	s_cbranch_scc1 .Lga_unit
	s_sub_u32 s0, s40, 144
	s_cmp_lt_u32 s0, 64
	s_cbranch_scc0 .Lga_done
	s_lshr_b32 s1, s0, 1
	s_add_u32 s1, s1, 0xe0
	s_and_b32 s0, s0, 1
	s_lshr_b32 s92, s21, 2
	s_cmp_lg_u32 s92, s0
	s_cselect_b32 s101, 3, 2
	s_branch .Lga_unit
.Lga_done:
	s_branch .LBB0_979
.Lsl_entry:
	s_cmp_eq_u32 s87, 1
	s_cbranch_scc1 .Lsl_run
	s_cmp_eq_u32 s87, 4
	s_cbranch_scc1 .Lsl_run
	s_cmp_eq_u32 s87, 5
	s_cbranch_scc1 .Lsl_chk
	s_cmp_eq_u32 s87, 7
	s_cbranch_scc0 .Lsl_skip
